# static priority 1 for waves 4-7 during the attention phase
# speedup vs baseline: 1.0119x; 1.0119x over previous
; #define VMW() asm volatile("s_waitcnt vmcnt(0)" ::: "memory")
; #define SLOAD_H(Kp, Vp, k0) do { S.st_v0 = load8(ROW(Vp, k0, sr)); S.st_v1 = load8(ROW(Vp, k0, 32 + sr)); S.st_k0 = load8(ROW(Kp, k0, sr)); S.st_k1 = load8(ROW(Kp, k0, 32 + sr)); } while (0)
; #define SWRITE_HK(bf) do { *(bf16x8*)(K_lds + (bf) * SHM_K + kws) = S.st_k0; *(bf16x8*)(K_lds + (bf) * SHM_K + kws + 32 * 256) = S.st_k1; } while (0)
; #define WSP(off) ((bf16*)((unsigned char*)kargp(25) + (off)))
; __device__ __forceinline__ void attn_prime(const BlockRef& cur, char* lds, Seam& S) {
;     int tid_ = threadIdx.x; asm volatile("" : "+v"(tid_));
;     const int tid = tid_, wid = __builtin_amdgcn_readfirstlane(tid >> 6), lane = tid & 63, r32 = lane & 31, hi = lane >> 5;
;     const int sr = tid >> 4, sc = (tid & 15) * 8, kws = KSWZ(sr, sc * 2); char* K_lds = lds + 2 * SHM_V;
;     for (int d0 = 0; d0 < 8; ++d0) S.qr[d0] = load8(cur.Q + (size_t)(wid * QBLK + r32) * D + d0 * 16 + hi * 8);
;     SLOAD_H(cur.K, cur.V, 0); VMW(); SWRITE_HK(0);
;     __syncthreads();
; }
; __global__ void __launch_bounds__(NTHR, 2) mega_fwd(Args args) {
;     ...
;         bf16* QH = WSP(WS_QH); bf16* KH = WSP(WS_KH); bf16* VH = WSP(WS_VH); bf16* O16 = WSP(WS_O16); bf16* OA = WSP(WS_OA);
;         att::Seam S;
;         const int NSI = BATCH * 4 * 16;
;         if (vcu < NSI) {
;             int si = vcu, sub = 0;
;     ...
;             att::BlockRef cur, nxt; MKREF(cur, si, sub);
;             att::attn_prime(cur, (char*)lds, S);
.LBB0_314:
	s_or_b64 exec, exec, s[14:15]
	s_nop 0
	s_nop 0
	s_nop 0
	s_nop 0
	s_nop 0
	s_nop 0
	s_nop 0
	s_nop 0
	s_nop 0
	s_waitcnt lgkmcnt(0)
	s_barrier
	s_movk_i32 s13, 0x100
	s_cmpk_lt_i32 s66, 0x100
	s_mov_b64 s[22:23], s[0:1]
	v_readfirstlane_b32 s24, v192
	s_mov_b64 s[20:21], s[0:1]
	s_mov_b64 s[18:19], s[0:1]
	s_mov_b64 s[14:15], s[0:1]
	s_mov_b64 s[16:17], s[0:1]
	s_cbranch_scc0 .LBB0_488
	s_bitcmp1_b32 s24, 8
	s_cbranch_scc0 .Lmy_noprio
	s_setprio 1
.Lmy_noprio:
	s_load_dwordx2 s[22:23], s[22:23], 0xc8
	v_mov_b32_e32 v1, v216
	s_load_dwordx2 s[20:21], s[20:21], 0xc8
	v_mov_b32_e32 v195, 0
	s_load_dwordx2 s[18:19], s[18:19], 0xc8
	s_waitcnt lgkmcnt(0)
	s_add_u32 s25, s22, 0x2f800000
	s_addc_u32 s26, s23, 0
	s_load_dwordx2 s[14:15], s[14:15], 0xc8
	s_add_u32 s27, s20, 0x33800000
	s_addc_u32 s28, s21, 0
	s_add_u32 s30, s18, 0x37800000
	s_addc_u32 s31, s19, 0
	s_waitcnt lgkmcnt(0)
	s_add_u32 s14, s14, 0xf800000
	s_addc_u32 s15, s15, 0
	s_bfe_u32 s20, s66, 0x20004
	s_ashr_i32 s21, s66, 6
	s_lshl_b32 s18, s20, 15
	s_lshl_b32 s19, s21, 17
	s_or_b32 s18, s18, s19
	s_lshl_b32 s19, s66, 8
	s_and_b32 s19, s19, 0xf00
	s_lshl_b32 s20, s20, 14
	s_lshl_b32 s21, s21, 16
	s_xor_b32 s29, s19, 0x1f00
	s_or_b32 s20, s20, s21
	s_or_b32 s18, s18, s29
	s_or_b32 s22, s20, s29
	s_ashr_i32 s19, s18, 31
	s_ashr_i32 s23, s22, 31
	s_lshl_b64 s[18:19], s[18:19], 8
	s_ashr_i32 s21, s20, 31
	s_lshl_b64 s[22:23], s[22:23], 8
	s_add_u32 s36, s25, s22
	s_addc_u32 s37, s26, s23
	s_lshl_b64 s[20:21], s[20:21], 8
	s_add_u32 s70, s27, s20
	s_addc_u32 s71, s28, s21
	s_add_u32 s72, s30, s20
	s_addc_u32 s73, s31, s21
	s_load_dwordx2 s[16:17], s[16:17], 0xc8
	s_add_u32 s22, s14, s18
	s_addc_u32 s23, s15, s19
	v_readfirstlane_b32 s18, v1
	s_ashr_i32 s18, s18, 1
	s_movk_i32 s19, 0xffe0
	v_mov_b32_e32 v2, s18
	v_bfi_b32 v2, s19, v2, v1
	v_ashrrev_i32_e32 v3, 31, v2
	v_lshlrev_b64 v[2:3], 8, v[2:3]
	s_waitcnt vmcnt(32)
	v_lshrrev_b32_e32 v4, 1, v1
	v_lshl_add_u64 v[2:3], s[36:37], 0, v[2:3]
	v_and_b32_e32 v194, 16, v4
	v_lshl_add_u64 v[2:3], v[2:3], 0, v[194:195]
	global_load_dwordx4 v[156:159], v[2:3], off
	global_load_dwordx4 v[152:155], v[2:3], off offset:32
	global_load_dwordx4 v[148:151], v[2:3], off offset:64
	global_load_dwordx4 v[144:147], v[2:3], off offset:96
	global_load_dwordx4 v[140:143], v[2:3], off offset:128
	global_load_dwordx4 v[136:139], v[2:3], off offset:160
	global_load_dwordx4 v[132:135], v[2:3], off offset:192
	global_load_dwordx4 v[128:131], v[2:3], off offset:224
	v_ashrrev_i32_e32 v2, 4, v1
	v_lshlrev_b32_e32 v3, 4, v1
	s_movk_i32 s18, 0xf0
	v_and_b32_e32 v1, 0x70, v1
	v_and_b32_e32 v194, 0xf0, v3
	v_bitop3_b32 v1, v3, v1, s18 bitop3:0x6c
	v_ashrrev_i32_e32 v3, 31, v2
	s_waitcnt vmcnt(37)
	v_lshlrev_b32_e32 v10, 8, v2
	v_lshlrev_b64 v[2:3], 8, v[2:3]
	v_lshl_add_u64 v[4:5], s[72:73], 0, v[2:3]
	s_mov_b64 s[18:19], 0x2000
	v_lshl_add_u64 v[4:5], v[4:5], 0, v[194:195]
	v_lshl_add_u64 v[6:7], v[2:3], 0, s[18:19]
	global_load_dwordx4 v[96:99], v[4:5], off
	v_lshl_add_u64 v[4:5], s[72:73], 0, v[6:7]
	v_lshl_add_u64 v[2:3], s[70:71], 0, v[2:3]
	v_lshl_add_u64 v[4:5], v[4:5], 0, v[194:195]
	v_lshl_add_u64 v[2:3], v[2:3], 0, v[194:195]
	v_lshl_add_u64 v[6:7], s[70:71], 0, v[6:7]
	global_load_dwordx4 v[100:103], v[4:5], off
	v_lshl_add_u64 v[6:7], v[6:7], 0, v[194:195]
	global_load_dwordx4 v[2:5], v[2:3], off
	v_writelane_b32 v254, s25, 53
	global_load_dwordx4 v[6:9], v[6:7], off
	v_add3_u32 v1, 0, v10, v1
	v_and_b32_e32 v255, 0x800, v10
	v_lshrrev_b32_e32 v255, 4, v255
	v_xor_b32_e32 v1, v1, v255
	v_writelane_b32 v254, s26, 54
	s_waitcnt vmcnt(0)
	v_writelane_b32 v254, s27, 55
	s_ashr_i32 s18, s24, 3
	v_writelane_b32 v254, s28, 56
	s_and_b32 s18, s18, -8
	v_and_b32_e32 v0, 63, v192
	v_writelane_b32 v254, s30, 57
	s_cmpk_lt_i32 s18, 0x200
	v_writelane_b32 v254, s31, 58
	s_mov_b32 s48, 0
	v_bfe_u32 v193, v192, 4, 2
	s_cselect_b64 s[24:25], -1, 0
	s_mov_b32 s67, 0x41000000
	s_mov_b32 s26, 0x3e0293ee
	v_mbcnt_hi_u32_b32 v205, -1, v217
	v_lshlrev_b32_e32 v214, 2, v0
	s_mov_b32 s28, 0x3f4ccccd
	s_mov_b32 s64, 0x200000
	s_mov_b32 s65, 0x400000
	s_mov_b32 s27, 0x600000
	v_mov_b32_e32 v218, 0x358637bd
	s_mov_b32 s47, 0xf800000
	v_mov_b32_e32 v219, 0x260
	v_mov_b32_e32 v220, 0xff800000
	v_mov_b32_e32 v221, 0xf149f2ca
	s_mov_b32 s77, 0
	v_writelane_b32 v254, s18, 59
	s_waitcnt vmcnt(1)
	ds_write_b128 v1, v[2:5] offset:32768
	s_waitcnt vmcnt(0)
	ds_write_b128 v1, v[6:9] offset:40960
	v_lshlrev_b32_e32 v1, 3, v192
	v_and_b32_e32 v2, 0x78, v1
	v_lshlrev_b32_e32 v194, 1, v2
	s_waitcnt lgkmcnt(0)
	v_lshl_add_u64 v[4:5], s[16:17], 0, v[194:195]
	s_mov_b64 s[16:17], 0x17800000
	v_lshl_add_u64 v[196:197], s[14:15], 0, v[194:195]
	v_lshl_add_u64 v[198:199], v[4:5], 0, s[16:17]
	v_lshlrev_b32_e32 v215, 2, v2
	s_barrier
	s_branch .LBB0_317

; __device__ __forceinline__ void xcd_barrier(const XcdBarrier& b) {
;     asm volatile("s_waitcnt vmcnt(0)" ::: "memory");
;     __syncthreads();
;     if (threadIdx.x == 0) {
;         unsigned* bar = b.bar;
;         __builtin_amdgcn_s_waitcnt(0);
;         unsigned nloc = b.st[0], nx = b.st[1];
;         if (nloc == 0u) { xcd_barrier_complete(bar, b.x, nloc, nx); b.st[0] = nloc; b.st[1] = nx; }
.LBB0_488:
	s_setprio 0
	s_waitcnt vmcnt(0)
	s_waitcnt lgkmcnt(0)
	s_barrier
	s_mov_b64 s[14:15], exec
	v_readlane_b32 s16, v254, 0
	v_readlane_b32 s17, v254, 1
	v_readlane_b32 s22, v254, 43
	s_and_b64 s[16:17], s[14:15], s[16:17]
	v_readlane_b32 s23, v254, 44
	s_mov_b64 exec, s[16:17]
	s_cbranch_execz .LBB0_540
	s_add_i32 s13, 0, 0x23f20
	v_mov_b32_e32 v0, s13
	s_waitcnt vmcnt(0) expcnt(0) lgkmcnt(0)
	ds_read_b32 v2, v0
	s_add_i32 s13, 0, 0x23f24
	v_mov_b32_e32 v0, s13
	ds_read_b32 v0, v0
	s_waitcnt lgkmcnt(1)
	v_cmp_ne_u32_e32 vcc, 0, v2
	s_cbranch_vccnz .LBB0_504
	s_mov_b32 s13, 1
	v_mov_b32_e32 v16, 0
	s_branch .LBB0_492

; #define PG8_WAIT_V(n) asm volatile("s_waitcnt vmcnt(" #n ")" ::: "memory")
; #define PG8_BAR __builtin_amdgcn_s_barrier()
; template <class Epi, class Sched, bool ALIGN_EPI = false, bool SP2 = false>
; __device__ __forceinline__ void gemm_phase(PG8_LAS unsigned char* lds, const Gemm g, const Sched& S, const Epi& E) {
;     int tid_ = threadIdx.x; asm volatile("" : "+v"(tid_));
;     const int tid = tid_, wid = __builtin_amdgcn_readfirstlane(tid >> 6), lane = tid & 63, wr = wid >> 2, wc = wid & 3, fr = lane & 15, fq = lane >> 4;
;     const int K = g.K, nt = K / BK;
;     unsigned voffA[2], voffB[2];
; #pragma unroll
;     for (int i = 0; i < 2; ++i) { int R, C; stage_rc(tid * 16 + i * 8192, R, C); const int Rb = Epi::PERM ? ((R & ~31) + perm32(R & 31)) : R;
;         voffA[i] = (unsigned)(R * K + C) * 2u; voffB[i] = (unsigned)(Rb * K + C) * 2u; }
;     const size_t kstep = (size_t)(BK * 2);
;     const size_t hstep = (size_t)HALF * K * 2;
;     const size_t tstep = 2 * hstep;
;     const unsigned ldsw = (unsigned)wid * 1024u;
;     const int aoff = lds_byte(wr * 64 + fr, fq * 8), boff = lds_byte(wc * 32 + fr, fq * 8);
;     ...
;     Unit cur, nxt; int ui = 0;
;     if (!S.next(0, cur)) return;
;     f32x4 acc[2][2][4][2];
; #pragma unroll
;     for (int a = 0; a < 2; ++a)
; #pragma unroll
;         for (int b = 0; b < 2; ++b)
; #pragma unroll
;             for (int m = 0; m < 4; ++m)
; #pragma unroll
;                 for (int n = 0; n < 2; ++n) acc[a][b][m][n] = (f32x4){0.f, 0.f, 0.f, 0.f};
;     bf16x8 At[4][2], B0[2][2], B1[2][2];
;     const char* cA = (const char*)g.A + (size_t)cur.pm * tstep; const char* cB = (const char*)g.Bt + (size_t)cur.pn * tstep;
;     S.a_ready(cur);
;     if constexpr (SP2) {
;         PG8_STAGE(PG8_SB(0, 0), cB, voffB); PG8_STAGE(PG8_SB(0, 1), cB + hstep, voffB); PG8_STAGE(PG8_SA(0, 0), cA, voffA); PG8_STAGE(PG8_SA(0, 1), cA + hstep, voffA);
;         if (wr == 1) PG8_BAR;
;         PG8_WAIT_V(2); PG8_BAR;
;         PG8_STAGE(PG8_SB(1, 0), cB + kstep, voffB); PG8_STAGE(PG8_SA(1, 0), cA + kstep, voffA); PG8_STAGE(PG8_SB(1, 1), cB + hstep + kstep, voffB);
;         PG8_WAIT_V(6); PG8_BAR;
;     } else {
;         PG8_STAGE(PG8_SB(0, 0), cB, voffB); PG8_STAGE(PG8_SA(0, 0), cA, voffA); PG8_STAGE(PG8_SB(0, 1), cB + hstep, voffB); PG8_STAGE(PG8_SA(0, 1), cA + hstep, voffA);
;         if (wr == 1) PG8_BAR;
;         PG8_WAIT_V(4); PG8_BAR;
.LBB0_540:
	s_or_b64 exec, exec, s[14:15]
	s_nop 0
	s_nop 0
	s_nop 0
	s_cmpk_lt_i32 s2, 0x400
	s_mov_b64 s[22:23], s[0:1]
	s_mov_b64 s[16:17], s[0:1]
	s_mov_b64 s[24:25], s[0:1]
	s_mov_b64 s[18:19], s[0:1]
	s_mov_b64 s[14:15], s[0:1]
	s_waitcnt lgkmcnt(0)
	s_barrier
	s_cselect_b64 s[48:49], -1, 0
	s_lshr_b32 s13, s33, 29
	s_add_i32 s13, s2, s13
	s_load_dwordx2 s[14:15], s[14:15], 0xc8
	s_ashr_i32 s56, s13, 3
	s_and_b32 s13, s13, -8
	s_load_dwordx2 s[20:21], s[16:17], 0xc8
	s_nop 0
	s_load_dwordx2 s[18:19], s[18:19], 0xc8
	s_mov_b64 s[16:17], s[0:1]
	s_sub_i32 s59, s2, s13
	s_cmp_lt_i32 s59, 0
	s_load_dwordx2 s[16:17], s[16:17], 0xc8
	s_cselect_b64 s[42:43], -1, 0
	s_lshl_b32 s57, s59, 7
	s_waitcnt lgkmcnt(0)
	s_add_u32 s14, s14, 0x2f800000
	s_addc_u32 s15, s15, 0
	s_waitcnt vmcnt(27)
	v_mov_b32_e32 v14, v216
	s_cmpk_gt_i32 s2, 0x3ff
	s_mul_i32 s58, s59, 0x81
	s_nop 0
	v_readfirstlane_b32 s28, v14
	s_cbranch_scc1 .LBB0_560
	v_lshlrev_b32_e32 v0, 4, v14
	v_add_u32_e32 v1, 0x2000, v0
	v_ashrrev_i32_e32 v2, 31, v1
	v_lshrrev_b32_e32 v2, 22, v2
	v_add_u32_e32 v2, v1, v2
	v_ashrrev_i32_e32 v8, 10, v2
	v_mul_i32_i24_e32 v2, 0x400, v8
	v_sub_u32_e32 v1, v1, v2
	v_lshrrev_b32_e32 v2, 4, v1
	v_bitop3_b32 v1, v2, v1, 32 bitop3:0x6c
	v_ashrrev_i32_e32 v2, 31, v1
	s_load_dwordx2 s[22:23], s[22:23], 0xc8
	s_nop 0
	s_load_dwordx2 s[24:25], s[24:25], 0xc8
	v_lshrrev_b32_e32 v2, 26, v2
	v_add_u32_e32 v2, v1, v2
	v_lshlrev_b32_e32 v3, 3, v8
	v_ashrrev_i32_e32 v9, 6, v2
	v_and_b32_e32 v3, -16, v3
	v_add_u32_e32 v3, v9, v3
	s_waitcnt lgkmcnt(0)
	s_add_u32 s13, s22, 0x3b800000
	v_and_b32_e32 v4, 3, v9
	s_mov_b32 s22, 0x1fffe0
	v_lshrrev_b32_e32 v5, 2, v3
	v_lshlrev_b32_e32 v6, 1, v3
	v_and_b32_e32 v2, 0xc0, v2
	v_and_or_b32 v4, v3, s22, v4
	v_and_b32_e32 v5, 4, v5
	v_and_b32_e32 v6, 24, v6
	v_sub_u32_e32 v1, v1, v2
	v_mov_b32_e32 v2, 1
	v_or3_b32 v4, v4, v5, v6
	v_lshlrev_b32_e32 v5, 5, v8
	v_ashrrev_i16_sdwa v1, v2, sext(v1) dst_sel:DWORD dst_unused:UNUSED_PAD src0_sel:DWORD src1_sel:BYTE_0
	v_and_b32_e32 v5, 32, v5
	v_bfe_i32 v10, v1, 0, 16
	v_add_lshl_u32 v1, v5, v10, 1
	s_waitcnt vmcnt(6)
	v_lshl_add_u32 v152, v4, 11, v1
	v_lshl_add_u32 v154, v3, 11, v1
	v_bfe_i32 v1, v14, 27, 1
	v_lshrrev_b32_e32 v1, 22, v1
	v_add_u32_e32 v1, v0, v1
	v_and_b32_e32 v1, 0xfffffc00, v1
	v_sub_u32_e32 v0, v0, v1
	v_lshrrev_b32_e32 v1, 4, v0
	v_ashrrev_i32_e32 v3, 31, v14
	v_bitop3_b32 v0, v1, v0, 32 bitop3:0x6c
	v_lshrrev_b32_e32 v3, 26, v3
	v_ashrrev_i32_e32 v1, 31, v0
	v_add_u32_e32 v3, v14, v3
	s_addc_u32 s47, s23, 0
	v_lshrrev_b32_e32 v1, 26, v1
	v_ashrrev_i32_e32 v12, 6, v3
	s_add_u32 s60, s24, 0x2600000
	v_add_u32_e32 v1, v0, v1
	v_lshlrev_b32_e32 v3, 3, v12
	s_addc_u32 s61, s25, 0
	s_ashr_i32 s26, s28, 6
	v_ashrrev_i32_e32 v11, 6, v1
	v_and_b32_e32 v3, -16, v3
	s_ashr_i32 s27, s28, 8
	s_lshl_b32 s62, s26, 10
	v_add_u32_e32 v3, v11, v3
	v_and_b32_e32 v4, 3, v11
	v_and_or_b32 v4, v3, s22, v4
	s_and_b64 s[22:23], s[42:43], exec
	s_cselect_b32 s22, s58, s57
	s_add_i32 s22, s22, s56
	s_ashr_i32 s23, s22, 31
	s_lshr_b32 s23, s23, 27
	s_add_i32 s23, s22, s23
	s_ashr_i32 s24, s23, 5
	s_and_b32 s23, s23, 0xffe0
	s_sub_i32 s22, s22, s23
	s_bfe_i32 s23, s22, 0x80000
	s_bfe_u32 s23, s23, 0x2000d
	s_add_i32 s23, s22, s23
	s_lshl_b32 s25, s24, 2
	s_bfe_i32 s24, s23, 0x80000
	s_and_b32 s23, s23, 0xfc
	s_sub_i32 s22, s22, s23
	s_sext_i32_i16 s24, s24
	s_sext_i32_i8 s22, s22
	v_lshrrev_b32_e32 v5, 2, v3
	v_lshlrev_b32_e32 v6, 1, v3
	v_and_b32_e32 v1, 0xc0, v1
	s_lshr_b32 s24, s24, 2
	s_add_i32 s44, s25, s22
	v_and_b32_e32 v5, 4, v5
	v_and_b32_e32 v6, 24, v6
	v_sub_u32_e32 v0, v0, v1
	s_ashr_i32 s45, s44, 31
	s_bfe_i64 s[30:31], s[24:25], 0x100000
	v_or3_b32 v4, v4, v5, v6
	v_lshlrev_b32_e32 v5, 5, v12
	v_ashrrev_i16_sdwa v0, v2, sext(v0) dst_sel:DWORD dst_unused:UNUSED_PAD src0_sel:DWORD src1_sel:BYTE_0
	s_lshl_b64 s[22:23], s[44:45], 19
	s_lshl_b64 s[30:31], s[30:31], 19
	v_and_b32_e32 v5, 32, v5
	v_bfe_i32 v13, v0, 0, 16
	s_add_u32 s52, s60, s30
	v_add_lshl_u32 v0, v5, v13, 1
	s_addc_u32 s53, s61, s31
	s_add_i32 s63, s62, 0
	v_lshl_add_u32 v156, v4, 11, v0
	s_add_i32 m0, s63, 0x10000
	v_lshl_add_u32 v158, v3, 11, v0
	global_load_lds_dwordx4 v156, s[52:53]
	s_add_i32 m0, s63, 0x12000
	s_add_u32 s30, s52, 0x40000
	global_load_lds_dwordx4 v152, s[52:53]
	s_addc_u32 s31, s53, 0
	s_add_i32 m0, s63, 0x14000
	v_mov_b32_e32 v157, 0
	global_load_lds_dwordx4 v156, s[30:31]
	s_add_i32 m0, s63, 0x16000
	s_add_u32 s50, s13, s22
	s_addc_u32 s51, s47, s23
	s_add_i32 s64, s63, 0x2000
	global_load_lds_dwordx4 v152, s[30:31]
	s_mov_b32 m0, s63
	s_add_u32 s22, s50, 0x40000
	global_load_lds_dwordx4 v158, s[50:51]
	s_mov_b32 m0, s64
	s_addc_u32 s23, s51, 0
	s_add_i32 s65, s63, 0x4000
	global_load_lds_dwordx4 v154, s[50:51]
	s_mov_b32 m0, s65
	s_add_i32 s66, s63, 0x6000
	global_load_lds_dwordx4 v158, s[22:23]
	s_mov_b32 m0, s66
	v_mov_b32_e32 v153, v157
	global_load_lds_dwordx4 v154, s[22:23]
	v_mov_b32_e32 v159, v157
	v_mov_b32_e32 v155, v157
	s_cmp_eq_u32 s27, 1
	v_lshl_add_u64 v[6:7], s[52:53], 0, v[156:157]
	v_lshl_add_u64 v[4:5], s[52:53], 0, v[152:153]
	v_lshl_add_u64 v[0:1], s[50:51], 0, v[158:159]
	s_cselect_b64 s[22:23], -1, 0
	s_cmp_lg_u32 s27, 1
	v_lshl_add_u64 v[2:3], s[50:51], 0, v[154:155]
	s_cbranch_scc1 .LBB0_543
	s_barrier
